# in-proj: per-unit preheader drain kept for the first unit only; first two counted waits after an epilogue relaxed to vmcnt(24) (every epilogue path issues at least 16 stores)
# speedup vs baseline: 1.0039x; 1.0039x over previous
; #define PG8_STAGE(bufoff, gbase, voff) do { _Pragma("unroll") for (int _i = 0; _i < 2; ++_i) \
;         __builtin_amdgcn_global_load_lds((const unsigned*)((const char*)(gbase) + (voff)[_i]), (PG8_LAS unsigned*)(lds + (bufoff) + ldsw + _i * 8192), 16, 0, 0); } while (0)
; #define PG8_LDA(dst, b, h) do { _Pragma("unroll") for (int m = 0; m < 4; ++m) _Pragma("unroll") for (int k = 0; k < 2; ++k) dst[m][k] = *(const PG8_LAS bf16x8*)(lds + PG8_SA(b, h) + aoff + m * 2048 + k * 1024); } while (0)
; #define PG8_LDB(dst, b, h) do { _Pragma("unroll") for (int n = 0; n < 2; ++n) _Pragma("unroll") for (int k = 0; k < 2; ++k) dst[n][k] = *(const PG8_LAS bf16x8*)(lds + PG8_SB(b, h) + boff + n * 2048 + k * 1024); } while (0)
; #define PG8_WAIT_V(n) asm volatile("s_waitcnt vmcnt(" #n ")" ::: "memory")
; #define PG8_WAIT_L(n) asm volatile("s_waitcnt lgkmcnt(" #n ")" ::: "memory")
; #define PG8_BAR __builtin_amdgcn_s_barrier()
; #define PG8_SCHED __builtin_amdgcn_sched_barrier(0)
; template <class Epi, class Sched, bool ALIGN_EPI = false, bool SP2 = false, class Hook = NoHook, bool REVK = false>
; __device__ __forceinline__ void gemm_phase(PG8_LAS unsigned char* lds, const Gemm g, const Sched& S, const Epi& E, const Hook H = Hook()) {
;     ...
;         const bool has_next = S.next(ui + 1, nxt);
;         const char* nA = has_next ? (const char*)g.A + (size_t)nxt.pm * tstep + krev : cA; const char* nB = has_next ? (const char*)g.Bt + (size_t)nxt.pn * tstep + krev : cB;
;         for (int t = 0; t < nt; t += 2) {
;             if constexpr (Hook::ENABLED) H(acc, t, nt, ui, wr, fr);
;             const bool last = (t == nt - 2);
;             const char* a1 = cA + (long)(t + 1) * kstep;
;             const char* a2 = last ? nA : cA + (long)(t + 2) * kstep; const char* b2 = last ? nB : cB + (long)(t + 2) * kstep;
;             const char* a3 = a2 + kstep; const char* b3 = b2 + kstep;
;             if (last && has_next) S.a_ready(nxt);
;             if constexpr (SP2) {
;             PG8_LDB(B0, 0, 0); PG8_LDB(B1, 0, 1); PG8_SCHED; PG8_LDA(At, 0, 0); PG8_STAGE(PG8_SA(1, 1), a1 + hstep, voffA);
;             PG8_WAIT_V(8); PG8_WAIT_L(0); PG8_BAR; PG8_MMA(0, 0, At, B0); PG8_MMA(0, 1, At, B1); PG8_BAR; PG8_SCHED;
;             PG8_LDA(At, 0, 1); PG8_STAGE(PG8_SB(0, 0), b2, voffB); PG8_STAGE(PG8_SB(0, 1), b2 + hstep, voffB); PG8_STAGE(PG8_SA(0, 0), a2, voffA);
.LBB0_58:
	s_ashr_i32 s93, s92, 31
	s_lshl_b64 s[22:23], s[92:93], 20
	s_add_u32 s94, s39, s22
	s_addc_u32 s95, s40, s23
	s_and_b64 s[22:23], s[6:7], exec
	s_cselect_b32 s29, s95, s27
	s_cselect_b32 s30, s94, s26
	s_ashr_i32 s91, s90, 31
	s_lshl_b64 s[22:23], s[90:91], 20
	s_add_u32 s96, s41, s22
	s_addc_u32 s97, s42, s23
	s_and_b64 s[22:23], s[6:7], exec
	s_cselect_b32 s31, s97, s21
	s_cselect_b32 s91, s96, s20
	s_add_u32 s22, s26, 0x80080
	s_addc_u32 s23, s27, 0
	s_add_u32 s93, s20, 0x100
	s_addc_u32 s98, s21, 0
	s_mov_b32 s99, -2
	s_cmp_lg_u32 s10, 0
	s_cbranch_scc1 .Lvw_in_d
	s_waitcnt vmcnt(0)
.Lvw_in_d:
	s_add_u32 s20, s22, 0xfff80080
	s_addc_u32 s21, s23, -1
	s_add_i32 s46, 0, 0x10000
	s_cmp_eq_u32 s99, 28
	s_cselect_b32 s27, s29, s21
	s_cselect_b32 s26, s30, s20
	s_cselect_b32 s21, s31, s98
	s_cselect_b32 s20, s91, s93
	s_add_i32 s58, 0, 0x14000
	v_add_u32_e32 v108, s46, v164
	v_add_u32_e32 v128, s58, v164
	ds_read_b128 v[96:99], v108
	ds_read_b128 v[100:103], v108 offset:1024
	ds_read_b128 v[104:107], v108 offset:2048
	ds_read_b128 v[108:111], v108 offset:3072
	ds_read_b128 v[182:185], v128
	ds_read_b128 v[186:189], v128 offset:1024
	ds_read_b128 v[190:193], v128 offset:2048
	ds_read_b128 v[194:197], v128 offset:3072
	v_lshl_add_u64 v[162:163], s[22:23], 0, v[158:159]
	s_add_i32 m0, s43, 0xc000
	ds_read_b128 v[200:203], v167
	ds_read_b128 v[204:207], v167 offset:1024
	ds_read_b128 v[210:213], v167 offset:2048
	ds_read_b128 v[226:229], v167 offset:3072
	ds_read_b128 v[230:233], v167 offset:4096
	ds_read_b128 v[234:237], v167 offset:5120
	ds_read_b128 v[238:241], v167 offset:6144
	ds_read_b128 v[242:245], v167 offset:7168
	global_load_lds_dwordx4 v[162:163], off
	v_lshl_add_u64 v[162:163], s[22:23], 0, v[160:161]
	s_add_i32 m0, s43, 0xe000
	s_nop 0
	global_load_lds_dwordx4 v[162:163], off
	s_cmp_lg_u32 s10, 0
	s_cbranch_scc1 .Lvw_in_0
	s_waitcnt vmcnt(8)
.Lvw_in_0:
	s_waitcnt vmcnt(24)
	s_waitcnt lgkmcnt(0)
	s_setprio 1
	s_barrier
	v_mfma_f32_16x16x32_bf16 v[142:145], v[96:99], v[200:203], 0
	v_mfma_f32_16x16x32_bf16 v[142:145], v[100:103], v[204:207], v[142:145]
	v_mfma_f32_16x16x32_bf16 v[138:141], v[108:111], v[204:207], 0
	v_mfma_f32_16x16x32_bf16 v[138:141], v[104:107], v[200:203], v[138:141]
	v_mfma_f32_16x16x32_bf16 v[130:133], v[182:185], v[200:203], 0
	v_mfma_f32_16x16x32_bf16 v[130:133], v[186:189], v[204:207], v[130:133]
	v_mfma_f32_16x16x32_bf16 v[134:137], v[194:197], v[204:207], 0
	v_mfma_f32_16x16x32_bf16 v[134:137], v[190:193], v[200:203], v[134:137]
	v_mfma_f32_16x16x32_bf16 v[124:127], v[190:193], v[210:213], 0
	v_mfma_f32_16x16x32_bf16 v[124:127], v[194:197], v[226:229], v[124:127]
	v_mfma_f32_16x16x32_bf16 v[112:115], v[186:189], v[226:229], 0
	v_mfma_f32_16x16x32_bf16 v[112:115], v[182:185], v[210:213], v[112:115]
	v_mfma_f32_16x16x32_bf16 v[120:123], v[104:107], v[210:213], 0
	v_mfma_f32_16x16x32_bf16 v[120:123], v[108:111], v[226:229], v[120:123]
	v_mfma_f32_16x16x32_bf16 v[116:119], v[100:103], v[226:229], 0
	v_mfma_f32_16x16x32_bf16 v[116:119], v[96:99], v[210:213], v[116:119]
	v_mfma_f32_16x16x32_bf16 v[84:87], v[96:99], v[230:233], 0
	v_mfma_f32_16x16x32_bf16 v[84:87], v[100:103], v[234:237], v[84:87]
	v_mfma_f32_16x16x32_bf16 v[88:91], v[108:111], v[234:237], 0
	v_mfma_f32_16x16x32_bf16 v[88:91], v[104:107], v[230:233], v[88:91]
	v_mfma_f32_16x16x32_bf16 v[80:83], v[182:185], v[230:233], 0
	v_mfma_f32_16x16x32_bf16 v[80:83], v[186:189], v[234:237], v[80:83]
	v_mfma_f32_16x16x32_bf16 v[92:95], v[194:197], v[234:237], 0
	v_mfma_f32_16x16x32_bf16 v[92:95], v[190:193], v[230:233], v[92:95]
	v_mfma_f32_16x16x32_bf16 v[76:79], v[190:193], v[238:241], 0
	v_mfma_f32_16x16x32_bf16 v[76:79], v[194:197], v[242:245], v[76:79]
	v_mfma_f32_16x16x32_bf16 v[64:67], v[186:189], v[242:245], 0
	v_mfma_f32_16x16x32_bf16 v[64:67], v[182:185], v[238:241], v[64:67]
	v_mfma_f32_16x16x32_bf16 v[72:75], v[104:107], v[238:241], 0
	v_mfma_f32_16x16x32_bf16 v[72:75], v[108:111], v[242:245], v[72:75]
	v_mfma_f32_16x16x32_bf16 v[68:71], v[100:103], v[242:245], 0
	v_mfma_f32_16x16x32_bf16 v[68:71], v[96:99], v[238:241], v[68:71]
	s_barrier
	s_setprio 0
	s_add_i32 s46, s46, s38
	v_lshl_add_u64 v[162:163], s[20:21], 0, v[150:151]
	s_mov_b32 m0, s46
	ds_read_b128 v[200:203], v167 offset:16384
	ds_read_b128 v[204:207], v167 offset:17408
	ds_read_b128 v[210:213], v167 offset:18432
	ds_read_b128 v[226:229], v167 offset:19456
	ds_read_b128 v[230:233], v167 offset:20480
	ds_read_b128 v[234:237], v167 offset:21504
	ds_read_b128 v[238:241], v167 offset:22528
	ds_read_b128 v[242:245], v167 offset:23552
	global_load_lds_dwordx4 v[162:163], off
	s_add_i32 m0, s46, 0x2000
	s_add_u32 s56, s20, 0x80000
	v_lshl_add_u64 v[168:169], s[20:21], 0, v[146:147]
	s_addc_u32 s57, s21, 0
	s_add_i32 s46, s58, s38
	global_load_lds_dwordx4 v[168:169], off
	v_lshl_add_u64 v[214:215], s[56:57], 0, v[150:151]
	s_mov_b32 m0, s46
	v_lshl_add_u64 v[246:247], s[26:27], 0, v[148:149]
	global_load_lds_dwordx4 v[214:215], off
	v_lshl_add_u64 v[214:215], s[56:57], 0, v[146:147]
	s_add_i32 m0, s46, 0x2000
	s_nop 0
	global_load_lds_dwordx4 v[214:215], off
	v_lshl_add_u64 v[214:215], s[26:27], 0, v[152:153]
	s_mov_b32 m0, s43
	s_nop 0
	global_load_lds_dwordx4 v[214:215], off
	s_mov_b32 m0, s75
	s_nop 0
	global_load_lds_dwordx4 v[246:247], off
	s_cmp_lg_u32 s10, 0
	s_cbranch_scc1 .Lvw_in_1
	s_waitcnt vmcnt(8)
; #define PG8_STAGE(bufoff, gbase, voff) do { _Pragma("unroll") for (int _i = 0; _i < 2; ++_i) \
;         __builtin_amdgcn_global_load_lds((const unsigned*)((const char*)(gbase) + (voff)[_i]), (PG8_LAS unsigned*)(lds + (bufoff) + ldsw + _i * 8192), 16, 0, 0); } while (0)
; #define PG8_LDA(dst, b, h) do { _Pragma("unroll") for (int m = 0; m < 4; ++m) _Pragma("unroll") for (int k = 0; k < 2; ++k) dst[m][k] = *(const PG8_LAS bf16x8*)(lds + PG8_SA(b, h) + aoff + m * 2048 + k * 1024); } while (0)
; #define PG8_LDB(dst, b, h) do { _Pragma("unroll") for (int n = 0; n < 2; ++n) _Pragma("unroll") for (int k = 0; k < 2; ++k) dst[n][k] = *(const PG8_LAS bf16x8*)(lds + PG8_SB(b, h) + boff + n * 2048 + k * 1024); } while (0)
; #define PG8_MMA(ai, bj, At, Bt) do { __builtin_amdgcn_s_setprio(1); _Pragma("unroll") for (int m = 0; m < 4; ++m) _Pragma("unroll") for (int n = 0; n < 2; ++n) _Pragma("unroll") for (int k = 0; k < 2; ++k) \
;         acc[ai][bj][m][n] = __builtin_amdgcn_mfma_f32_16x16x32_bf16(Bt[n][k], At[m][k], acc[ai][bj][m][n], 0, 0, 0); __builtin_amdgcn_s_setprio(0); } while (0)
; #define PG8_WAIT_V(n) asm volatile("s_waitcnt vmcnt(" #n ")" ::: "memory")
; #define PG8_WAIT_L(n) asm volatile("s_waitcnt lgkmcnt(" #n ")" ::: "memory")
; #define PG8_BAR __builtin_amdgcn_s_barrier()
; #define PG8_SCHED __builtin_amdgcn_sched_barrier(0)
; template <class Epi, class Sched, bool ALIGN_EPI = false, bool SP2 = false, class Hook = NoHook, bool REVK = false>
; __device__ __forceinline__ void gemm_phase(PG8_LAS unsigned char* lds, const Gemm g, const Sched& S, const Epi& E, const Hook H = Hook()) {
;     ...
;             PG8_WAIT_V(8); PG8_WAIT_L(0); PG8_BAR; PG8_MMA(1, 0, At, B0); PG8_MMA(1, 1, At, B1); PG8_BAR; PG8_SCHED;
;             PG8_LDB(B0, 1, 0); PG8_LDB(B1, 1, 1); PG8_SCHED; PG8_LDA(At, 1, 0); PG8_STAGE(PG8_SA(0, 1), a2 + hstep, voffA);
;             PG8_WAIT_V(8); PG8_WAIT_L(0); PG8_BAR; PG8_MMA(0, 0, At, B0); PG8_MMA(0, 1, At, B1); PG8_BAR; PG8_SCHED;
.Lvw_in_1:
	s_waitcnt vmcnt(24)
	s_waitcnt lgkmcnt(0)
	s_setprio 1
	s_barrier
	v_mfma_f32_16x16x32_bf16 v[52:55], v[96:99], v[200:203], 0
	v_mfma_f32_16x16x32_bf16 v[52:55], v[100:103], v[204:207], v[52:55]
	v_mfma_f32_16x16x32_bf16 v[56:59], v[108:111], v[204:207], 0
	v_mfma_f32_16x16x32_bf16 v[56:59], v[104:107], v[200:203], v[56:59]
	v_mfma_f32_16x16x32_bf16 v[48:51], v[182:185], v[200:203], 0
	v_mfma_f32_16x16x32_bf16 v[48:51], v[186:189], v[204:207], v[48:51]
	v_mfma_f32_16x16x32_bf16 v[60:63], v[194:197], v[204:207], 0
	v_mfma_f32_16x16x32_bf16 v[60:63], v[190:193], v[200:203], v[60:63]
	v_mfma_f32_16x16x32_bf16 v[44:47], v[190:193], v[210:213], 0
	v_mfma_f32_16x16x32_bf16 v[44:47], v[194:197], v[226:229], v[44:47]
	v_mfma_f32_16x16x32_bf16 v[32:35], v[186:189], v[226:229], 0
	v_mfma_f32_16x16x32_bf16 v[32:35], v[182:185], v[210:213], v[32:35]
	v_mfma_f32_16x16x32_bf16 v[40:43], v[104:107], v[210:213], 0
	v_mfma_f32_16x16x32_bf16 v[40:43], v[108:111], v[226:229], v[40:43]
	v_mfma_f32_16x16x32_bf16 v[36:39], v[100:103], v[226:229], 0
	v_mfma_f32_16x16x32_bf16 v[36:39], v[96:99], v[210:213], v[36:39]
	v_mfma_f32_16x16x32_bf16 v[20:23], v[96:99], v[230:233], 0
	v_mfma_f32_16x16x32_bf16 v[20:23], v[100:103], v[234:237], v[20:23]
	v_mfma_f32_16x16x32_bf16 v[24:27], v[108:111], v[234:237], 0
	v_mfma_f32_16x16x32_bf16 v[24:27], v[104:107], v[230:233], v[24:27]
	v_mfma_f32_16x16x32_bf16 v[16:19], v[182:185], v[230:233], 0
	v_mfma_f32_16x16x32_bf16 v[16:19], v[186:189], v[234:237], v[16:19]
	v_mfma_f32_16x16x32_bf16 v[28:31], v[194:197], v[234:237], 0
	v_mfma_f32_16x16x32_bf16 v[28:31], v[190:193], v[230:233], v[28:31]
	v_mfma_f32_16x16x32_bf16 v[12:15], v[190:193], v[238:241], 0
	v_mfma_f32_16x16x32_bf16 v[12:15], v[194:197], v[242:245], v[12:15]
	v_mfma_f32_16x16x32_bf16 v[0:3], v[186:189], v[242:245], 0
	v_mfma_f32_16x16x32_bf16 v[0:3], v[182:185], v[238:241], v[0:3]
	v_mfma_f32_16x16x32_bf16 v[8:11], v[104:107], v[238:241], 0
	v_mfma_f32_16x16x32_bf16 v[8:11], v[108:111], v[242:245], v[8:11]
	v_mfma_f32_16x16x32_bf16 v[4:7], v[100:103], v[242:245], 0
	v_mfma_f32_16x16x32_bf16 v[4:7], v[96:99], v[238:241], v[4:7]
	s_barrier
	s_setprio 0
	s_add_i32 s46, 0, 0x18000
	s_add_i32 s56, 0, 0x1c000
	v_add_u32_e32 v108, s46, v164
	v_add_u32_e32 v128, s56, v164
	ds_read_b128 v[96:99], v108
	ds_read_b128 v[100:103], v108 offset:1024
	ds_read_b128 v[104:107], v108 offset:2048
	ds_read_b128 v[108:111], v108 offset:3072
	ds_read_b128 v[182:185], v128
	ds_read_b128 v[186:189], v128 offset:1024
	ds_read_b128 v[190:193], v128 offset:2048
	ds_read_b128 v[194:197], v128 offset:3072
	s_add_u32 s26, s26, 0x80000
	s_addc_u32 s27, s27, 0
	s_mov_b32 m0, s77
	v_lshl_add_u64 v[248:249], s[26:27], 0, v[152:153]
	ds_read_b128 v[200:203], v167 offset:32768
	ds_read_b128 v[204:207], v167 offset:33792
	ds_read_b128 v[210:213], v167 offset:34816
	ds_read_b128 v[226:229], v167 offset:35840
	ds_read_b128 v[230:233], v167 offset:36864
	ds_read_b128 v[234:237], v167 offset:37888
	ds_read_b128 v[238:241], v167 offset:38912
	ds_read_b128 v[242:245], v167 offset:39936
	global_load_lds_dwordx4 v[248:249], off
	v_lshl_add_u64 v[248:249], s[26:27], 0, v[148:149]
	s_mov_b32 m0, s79
	s_nop 0
	global_load_lds_dwordx4 v[248:249], off
	s_waitcnt vmcnt(8)
	s_waitcnt lgkmcnt(0)
	s_setprio 1
	s_barrier
	v_mfma_f32_16x16x32_bf16 v[142:145], v[96:99], v[200:203], v[142:145]
	v_mfma_f32_16x16x32_bf16 v[142:145], v[100:103], v[204:207], v[142:145]
	v_mfma_f32_16x16x32_bf16 v[138:141], v[108:111], v[204:207], v[138:141]
	v_mfma_f32_16x16x32_bf16 v[138:141], v[104:107], v[200:203], v[138:141]
	v_mfma_f32_16x16x32_bf16 v[130:133], v[182:185], v[200:203], v[130:133]
	v_mfma_f32_16x16x32_bf16 v[130:133], v[186:189], v[204:207], v[130:133]
	v_mfma_f32_16x16x32_bf16 v[134:137], v[194:197], v[204:207], v[134:137]
	v_mfma_f32_16x16x32_bf16 v[134:137], v[190:193], v[200:203], v[134:137]
	v_mfma_f32_16x16x32_bf16 v[124:127], v[190:193], v[210:213], v[124:127]
	v_mfma_f32_16x16x32_bf16 v[124:127], v[194:197], v[226:229], v[124:127]
	v_mfma_f32_16x16x32_bf16 v[112:115], v[186:189], v[226:229], v[112:115]
	v_mfma_f32_16x16x32_bf16 v[112:115], v[182:185], v[210:213], v[112:115]
	v_mfma_f32_16x16x32_bf16 v[120:123], v[104:107], v[210:213], v[120:123]
	v_mfma_f32_16x16x32_bf16 v[120:123], v[108:111], v[226:229], v[120:123]
	v_mfma_f32_16x16x32_bf16 v[116:119], v[100:103], v[226:229], v[116:119]
	v_mfma_f32_16x16x32_bf16 v[116:119], v[96:99], v[210:213], v[116:119]
	v_mfma_f32_16x16x32_bf16 v[84:87], v[96:99], v[230:233], v[84:87]
	v_mfma_f32_16x16x32_bf16 v[84:87], v[100:103], v[234:237], v[84:87]
	v_mfma_f32_16x16x32_bf16 v[88:91], v[108:111], v[234:237], v[88:91]
	v_mfma_f32_16x16x32_bf16 v[88:91], v[104:107], v[230:233], v[88:91]
	v_mfma_f32_16x16x32_bf16 v[80:83], v[182:185], v[230:233], v[80:83]
	v_mfma_f32_16x16x32_bf16 v[80:83], v[186:189], v[234:237], v[80:83]
	v_mfma_f32_16x16x32_bf16 v[92:95], v[194:197], v[234:237], v[92:95]
	v_mfma_f32_16x16x32_bf16 v[92:95], v[190:193], v[230:233], v[92:95]
	v_mfma_f32_16x16x32_bf16 v[76:79], v[190:193], v[238:241], v[76:79]
	v_mfma_f32_16x16x32_bf16 v[76:79], v[194:197], v[242:245], v[76:79]
	v_mfma_f32_16x16x32_bf16 v[64:67], v[186:189], v[242:245], v[64:67]
	v_mfma_f32_16x16x32_bf16 v[64:67], v[182:185], v[238:241], v[64:67]
	v_mfma_f32_16x16x32_bf16 v[72:75], v[104:107], v[238:241], v[72:75]
	v_mfma_f32_16x16x32_bf16 v[72:75], v[108:111], v[242:245], v[72:75]
	v_mfma_f32_16x16x32_bf16 v[68:71], v[100:103], v[242:245], v[68:71]
	v_mfma_f32_16x16x32_bf16 v[68:71], v[96:99], v[238:241], v[68:71]
	s_barrier
; #define PG8_STAGE(bufoff, gbase, voff) do { _Pragma("unroll") for (int _i = 0; _i < 2; ++_i) \
;         __builtin_amdgcn_global_load_lds((const unsigned*)((const char*)(gbase) + (voff)[_i]), (PG8_LAS unsigned*)(lds + (bufoff) + ldsw + _i * 8192), 16, 0, 0); } while (0)
; #define PG8_LDA(dst, b, h) do { _Pragma("unroll") for (int m = 0; m < 4; ++m) _Pragma("unroll") for (int k = 0; k < 2; ++k) dst[m][k] = *(const PG8_LAS bf16x8*)(lds + PG8_SA(b, h) + aoff + m * 2048 + k * 1024); } while (0)
; #define PG8_MMA(ai, bj, At, Bt) do { __builtin_amdgcn_s_setprio(1); _Pragma("unroll") for (int m = 0; m < 4; ++m) _Pragma("unroll") for (int n = 0; n < 2; ++n) _Pragma("unroll") for (int k = 0; k < 2; ++k) \
;         acc[ai][bj][m][n] = __builtin_amdgcn_mfma_f32_16x16x32_bf16(Bt[n][k], At[m][k], acc[ai][bj][m][n], 0, 0, 0); __builtin_amdgcn_s_setprio(0); } while (0)
; #define PG8_WAIT_V(n) asm volatile("s_waitcnt vmcnt(" #n ")" ::: "memory")
; #define PG8_WAIT_L(n) asm volatile("s_waitcnt lgkmcnt(" #n ")" ::: "memory")
; #define PG8_BAR __builtin_amdgcn_s_barrier()
; #define PG8_SCHED __builtin_amdgcn_sched_barrier(0)
; template <class Epi, class Sched, bool ALIGN_EPI = false, bool SP2 = false, class Hook = NoHook, bool REVK = false>
; __device__ __forceinline__ void gemm_phase(PG8_LAS unsigned char* lds, const Gemm g, const Sched& S, const Epi& E, const Hook H = Hook()) {
;     ...
;         for (int t = 0; t < nt; t += 2) {
;     ...
;             PG8_LDA(At, 1, 1); PG8_STAGE(PG8_SB(1, 0), b3, voffB); PG8_STAGE(PG8_SB(1, 1), b3 + hstep, voffB); PG8_STAGE(PG8_SA(1, 0), a3, voffA);
;             PG8_WAIT_V(8); PG8_WAIT_L(0); PG8_BAR; PG8_MMA(1, 0, At, B0); PG8_MMA(1, 1, At, B1); PG8_BAR; PG8_SCHED;
	s_setprio 0
	s_add_i32 s26, s46, s38
	v_lshl_add_u64 v[162:163], v[162:163], 0, s[64:65]
	s_mov_b32 m0, s26
	ds_read_b128 v[200:203], v167 offset:49152
	ds_read_b128 v[204:207], v167 offset:50176
	ds_read_b128 v[210:213], v167 offset:51200
	ds_read_b128 v[226:229], v167 offset:52224
	ds_read_b128 v[230:233], v167 offset:53248
	ds_read_b128 v[234:237], v167 offset:54272
	ds_read_b128 v[238:241], v167 offset:55296
	ds_read_b128 v[242:245], v167 offset:56320
	global_load_lds_dwordx4 v[162:163], off
	s_add_i32 m0, s26, 0x2000
	s_add_u32 s20, s20, 0x80080
	v_lshl_add_u64 v[162:163], v[168:169], 0, s[64:65]
	s_addc_u32 s21, s21, 0
	s_add_i32 s26, s56, s38
	global_load_lds_dwordx4 v[162:163], off
	v_lshl_add_u64 v[162:163], s[20:21], 0, v[150:151]
	s_mov_b32 m0, s26
	s_nop 0
	global_load_lds_dwordx4 v[162:163], off
	v_lshl_add_u64 v[162:163], s[20:21], 0, v[146:147]
	s_add_i32 m0, s26, 0x2000
	s_nop 0
	global_load_lds_dwordx4 v[162:163], off
	v_lshl_add_u64 v[162:163], v[214:215], 0, s[64:65]
	s_mov_b32 m0, s44
	s_nop 0
	global_load_lds_dwordx4 v[162:163], off
	v_lshl_add_u64 v[162:163], v[246:247], 0, s[64:65]
	s_mov_b32 m0, s36
	s_nop 0
	global_load_lds_dwordx4 v[162:163], off
	s_waitcnt vmcnt(8)
	s_waitcnt lgkmcnt(0)
	s_setprio 1
	s_barrier
	v_mfma_f32_16x16x32_bf16 v[52:55], v[96:99], v[200:203], v[52:55]
	v_mfma_f32_16x16x32_bf16 v[52:55], v[100:103], v[204:207], v[52:55]
	v_mfma_f32_16x16x32_bf16 v[56:59], v[108:111], v[204:207], v[56:59]
	v_mfma_f32_16x16x32_bf16 v[56:59], v[104:107], v[200:203], v[56:59]
	v_mfma_f32_16x16x32_bf16 v[48:51], v[182:185], v[200:203], v[48:51]
	v_mfma_f32_16x16x32_bf16 v[48:51], v[186:189], v[204:207], v[48:51]
	v_mfma_f32_16x16x32_bf16 v[60:63], v[194:197], v[204:207], v[60:63]
	v_mfma_f32_16x16x32_bf16 v[60:63], v[190:193], v[200:203], v[60:63]
	v_mfma_f32_16x16x32_bf16 v[44:47], v[190:193], v[210:213], v[44:47]
	v_mfma_f32_16x16x32_bf16 v[44:47], v[194:197], v[226:229], v[44:47]
	v_mfma_f32_16x16x32_bf16 v[32:35], v[186:189], v[226:229], v[32:35]
	v_mfma_f32_16x16x32_bf16 v[32:35], v[182:185], v[210:213], v[32:35]
	v_mfma_f32_16x16x32_bf16 v[40:43], v[104:107], v[210:213], v[40:43]
	v_mfma_f32_16x16x32_bf16 v[40:43], v[108:111], v[226:229], v[40:43]
	v_mfma_f32_16x16x32_bf16 v[36:39], v[100:103], v[226:229], v[36:39]
	v_mfma_f32_16x16x32_bf16 v[36:39], v[96:99], v[210:213], v[36:39]
	v_mfma_f32_16x16x32_bf16 v[20:23], v[96:99], v[230:233], v[20:23]
	v_mfma_f32_16x16x32_bf16 v[20:23], v[100:103], v[234:237], v[20:23]
	v_mfma_f32_16x16x32_bf16 v[24:27], v[108:111], v[234:237], v[24:27]
	v_mfma_f32_16x16x32_bf16 v[24:27], v[104:107], v[230:233], v[24:27]
	v_mfma_f32_16x16x32_bf16 v[16:19], v[182:185], v[230:233], v[16:19]
	v_mfma_f32_16x16x32_bf16 v[16:19], v[186:189], v[234:237], v[16:19]
	v_mfma_f32_16x16x32_bf16 v[28:31], v[194:197], v[234:237], v[28:31]
	v_mfma_f32_16x16x32_bf16 v[28:31], v[190:193], v[230:233], v[28:31]
	v_mfma_f32_16x16x32_bf16 v[12:15], v[190:193], v[238:241], v[12:15]
	v_mfma_f32_16x16x32_bf16 v[12:15], v[194:197], v[242:245], v[12:15]
	v_mfma_f32_16x16x32_bf16 v[0:3], v[186:189], v[242:245], v[0:3]
	v_mfma_f32_16x16x32_bf16 v[0:3], v[182:185], v[238:241], v[0:3]
	v_mfma_f32_16x16x32_bf16 v[8:11], v[104:107], v[238:241], v[8:11]
	v_mfma_f32_16x16x32_bf16 v[8:11], v[108:111], v[242:245], v[8:11]
	v_mfma_f32_16x16x32_bf16 v[4:7], v[100:103], v[242:245], v[4:7]
	v_mfma_f32_16x16x32_bf16 v[4:7], v[96:99], v[238:241], v[4:7]
	s_barrier
	s_setprio 0
	s_add_i32 s99, s99, 2
	s_add_u32 s22, s22, 0x100
	s_addc_u32 s23, s23, 0
	s_add_u32 s93, s93, 0x100
	s_addc_u32 s98, s98, 0
	s_cmp_gt_u32 s99, 29
